# Z1: the two remaining no-op steps (45 and 53) added to the step-skip mask for the 256-workgroup grid; byte layout unchanged; on top of K1+R1+S1
# baseline (speedup 1.0000x reference)
; __global__ void __launch_bounds__(NTHR, 2) dit_fwd(Args args) {
;     ...
;         int kind = ST_NOP, l = 0, sub = -1, rw = 0, coff = 0; bool seam = false;
;         if (st == 0) { kind = ST_PRO; seam = true; }
;         else if (st == 1) { kind = ST_ROW; rw = 0; seam = true; }
;         else if (st >= N_STEPS) { seam = true; }
;         else { l = (st - 2) / STEPS_PER_LAYER; sub = (st - 2) % STEPS_PER_LAYER; }
;         const bool even = (l & 1) == 0; const int eo = l >> 1;
;         const bool fuse = G == 256;
;         const bool ctx_live = l < 2;
;         const int nrows = ctx_live ? MT : MX, nMt = nrows / 256;
;         gm::Call C{}; C.G = G;
;         if (sub == 0) {
;             kind = ST_GEMM; C.K = DM; C.lda = DM; C.ldb = DM;
;             if (even) C.j0 = gm::Job{HX, (const bf16_t*)(ws + WS_WIN + eo * SZ_WIN), BIG, (const float*)(ws + WS_TAB), nullptr, nMt, ATT_IN / 256, gm::K_ROPE, ATT_IN, 0, 0, 0, 0, 1, nullptr};
;             else C.j0 = gm::Job{(const bf16_t*)(ws + WS_WMI + eo * SZ_WMI) + (size_t)512 * DM, HX, ws + WS_VT, nullptr, ws + WS_VTC, 4, nMt, gm::K_VT, 0, 0, 0, 0, 0, 1, nullptr};
;         } else if (sub == 1) {
;             seam = true; C.K = DM; C.lda = DM; C.ldb = DM;
;             if (!even) { kind = ST_GEMM; coff = (4 * nMt) % G; C.j0 = gm::Job{HX, (const bf16_t*)(ws + WS_WMI + eo * SZ_WMI), ws + WS_UPOOL, nullptr, nullptr, nMt, 2, gm::K_PLAIN, 512, 0, 0, 0, 0, 1, nullptr}; }
;             else if (l == 2) { kind = ST_GEMM; coff = (64 * 9) % G;
;                 C.j0 = gm::Job{HX + (size_t)MX * DM, (const bf16_t*)(ws + WS_WIN + eo * SZ_WIN) + (size_t)512 * DM, BIG, (const float*)(ws + WS_TAB), nullptr, MC / 256, 1, gm::K_ROPE, ATT_IN, MX, 512, 0, 0, 1, nullptr}; }
;         } else if (sub == 2) {
;             if (even) { kind = ST_ATT; seam = true; }
;             else { kind = ST_GEMM; C.K = SEQ; C.lda = 2 * SEQ; C.ldb = 2 * SEQ;
;                 C.j0 = gm::Job{(const bf16_t*)(ws + WS_FMAT), (const bf16_t*)(ws + WS_VT), nullptr, nullptr, nullptr, 0, 16, gm::K_PLAIN, 0, 0, 0, 1, 4, 2, (float*)(ws + WS_DSLAB)}; }
;         } else if (sub == 3) {
;             if (!even) { kind = ST_GEMM; coff = 128 % G; C.K = SEQ; C.lda = 2 * SEQ; C.ldb = 2 * SEQ;
.Lp3_fused:
	s_mov_b32 vcc_lo, 0x800001e0
	s_mov_b32 vcc_hi, 0x222117
